# v15 + back-edge rotation (tail SALU hoisted before last barrier, one taken branch) with 64-byte aligned steady body
# baseline (speedup 1.0000x reference)
.Lrot_rare_ine:
	s_mov_b32 m0, s59
	s_nop 0
	global_load_lds_dwordx4 v[142:143], off
	s_mov_b32 m0, s60
	s_nop 0
	global_load_lds_dwordx4 v[144:145], off
	s_branch .Lrot_body_ine
	.p2align	6

.Lrot_rare_ino:
	s_mov_b32 m0, s59
	s_nop 0
	global_load_lds_dwordx4 v[130:131], off
	s_mov_b32 m0, s60
	s_nop 0
	global_load_lds_dwordx4 v[132:133], off
	s_branch .Lrot_body_ino
	.p2align	6

.Lrot_rare_out:
	s_mov_b32 m0, s59
	s_nop 0
	global_load_lds_dwordx4 v[70:71], off
	s_mov_b32 m0, s60
	s_nop 0
	global_load_lds_dwordx4 v[72:73], off
	s_branch .Lrot_body_out
	.p2align	6

.Lrot_rare_gu:
	s_mov_b32 m0, s59
	s_nop 0
	global_load_lds_dwordx4 v[140:141], off
	s_mov_b32 m0, s60
	s_nop 0
	global_load_lds_dwordx4 v[142:143], off
	s_branch .Lrot_body_gu
	.p2align	6

.Lrot_rare_down:
	s_mov_b32 m0, s59
	s_nop 0
	global_load_lds_dwordx4 v[66:67], off
	s_mov_b32 m0, s60
	s_nop 0
	global_load_lds_dwordx4 v[68:69], off
	s_branch .Lrot_body_down
	.p2align	6
